# P0: the eight context-filter units are split into sixteen half units (512 channel columns each) so that no workgroup runs two full filter units back to back
# speedup vs baseline: 1.0161x; 1.0111x over previous
.LBB0_5:
	s_or_b64 exec, exec, s[4:5]
	s_load_dwordx16 s[4:19], s[0:1], 0x0
	s_add_u32 s30, s72, 0x100000
	s_addc_u32 s31, s73, 0
	v_mov_b32_e32 v2, v170
	v_lshrrev_b32_e32 v223, 4, v170
	s_waitcnt lgkmcnt(0)
	v_writelane_b32 v251, s4, 22
	v_lshlrev_b32_e32 v226, 4, v170
	v_lshrrev_b32_e32 v222, 6, v170
	v_writelane_b32 v251, s5, 23
	v_writelane_b32 v251, s6, 24
	v_writelane_b32 v251, s7, 25
	v_writelane_b32 v251, s8, 26
	v_writelane_b32 v251, s9, 27
	v_writelane_b32 v251, s10, 28
	v_writelane_b32 v251, s11, 29
	v_writelane_b32 v251, s12, 30
	v_writelane_b32 v251, s13, 31
	v_writelane_b32 v251, s14, 32
	v_writelane_b32 v251, s15, 33
	v_writelane_b32 v251, s16, 34
	v_writelane_b32 v251, s17, 35
	v_writelane_b32 v251, s18, 36
	v_writelane_b32 v251, s19, 37
	s_load_dwordx16 s[4:19], s[0:1], 0x80
	s_add_u32 s0, s72, 0x400000
	s_addc_u32 s1, s73, 0
	v_lshrrev_b32_e32 v224, 3, v170
	v_lshlrev_b32_e32 v225, 3, v170
	s_waitcnt lgkmcnt(0)
	v_writelane_b32 v251, s4, 38
	s_nop 1
	v_writelane_b32 v251, s5, 39
	v_writelane_b32 v251, s6, 40
	v_writelane_b32 v251, s7, 41
	v_writelane_b32 v251, s8, 42
	v_writelane_b32 v251, s9, 43
	v_writelane_b32 v251, s10, 44
	v_writelane_b32 v251, s11, 45
	v_writelane_b32 v251, s12, 46
	v_writelane_b32 v251, s13, 47
	v_writelane_b32 v251, s14, 48
	v_writelane_b32 v251, s15, 49
	v_writelane_b32 v251, s16, 50
	v_writelane_b32 v251, s17, 51
	v_writelane_b32 v251, s18, 52
	v_writelane_b32 v251, s19, 53
	v_writelane_b32 v251, s0, 54
	s_nop 1
	v_writelane_b32 v251, s1, 55
	s_add_u32 s0, s72, 0x4900000
	s_addc_u32 s1, s73, 0
	v_writelane_b32 v251, s0, 56
	s_nop 1
	v_writelane_b32 v251, s1, 57
	s_add_u32 s0, s72, 0x6900000
	s_addc_u32 s1, s73, 0
	s_add_u32 s10, s72, 0x6a00000
	v_writelane_b32 v251, s0, 58
	s_addc_u32 s11, s73, 0
	s_cmpk_gt_i32 s64, 0xd1f
	v_writelane_b32 v251, s1, 59
	s_cbranch_scc1 .LBB0_77
	v_and_b32_e32 v4, 0xf0, v226
	v_and_b32_e32 v230, 63, v170
	s_movk_i32 s0, 0x90
	v_lshl_or_b32 v3, v223, 8, v4
	v_lshlrev_b32_e32 v8, 2, v230
	v_and_b32_e32 v50, 56, v225
	v_mov_b32_e32 v41, 0
	v_lshlrev_b32_e32 v40, 2, v170
	v_readlane_b32 s36, v251, 2
	v_readlane_b32 s76, v251, 38
	v_mad_u32_u24 v227, v223, s0, 16
	v_add_u32_e32 v228, 16, v3
	v_add_u32_e32 v229, 0xffe80000, v2
	v_add_u32_e32 v9, 16, v8
	s_movk_i32 s0, 0x300
	v_mul_u32_u24_e32 v2, 0x104, v50
	v_lshlrev_b32_e32 v3, 2, v224
	v_readlane_b32 s37, v251, 3
	v_readlane_b32 s38, v251, 4
	v_readlane_b32 s39, v251, 5
	v_readlane_b32 s40, v251, 6
	v_readlane_b32 s41, v251, 7
	v_readlane_b32 s42, v251, 8
	v_readlane_b32 s43, v251, 9
	v_readlane_b32 s77, v251, 39
	v_mad_u32_u24 v231, v222, s0, v9
	s_movk_i32 s0, 0xc0
	v_mov_b32_e32 v5, v41
	v_add3_u32 v234, 16, v2, v3
	v_or_b32_e32 v2, 0x1000, v40
	v_mov_b32_e32 v3, v41
	v_add_u32_e32 v51, 16, v4
	v_cmp_gt_u32_e64 s[4:5], s0, v170
	s_add_u32 s0, s72, 0x1280000
	v_lshl_add_u64 v[48:49], s[38:39], 0, v[4:5]
	v_lshl_add_u64 v[52:53], s[36:37], 0, v[4:5]
	v_lshl_add_u64 v[54:55], s[42:43], 0, v[4:5]
	v_lshl_add_u64 v[56:57], s[40:41], 0, v[4:5]
	v_lshl_add_u64 v[60:61], s[76:77], 0, v[2:3]
	v_or_b32_e32 v2, 0x2000, v40
	v_or_b32_e32 v4, 0xc00, v170
	s_addc_u32 s1, s73, 0
	v_lshl_add_u64 v[64:65], s[76:77], 0, v[2:3]
	v_lshlrev_b32_e32 v2, 2, v4
	s_add_u32 s12, s72, 0xa80000
	v_lshl_add_u64 v[68:69], s[76:77], 0, v[2:3]
	v_and_b32_e32 v2, 15, v170
	v_readlane_b32 s44, v251, 10
	v_readlane_b32 s45, v251, 11
	v_readlane_b32 s46, v251, 12
	v_readlane_b32 s47, v251, 13
	v_readlane_b32 s48, v251, 14
	v_readlane_b32 s49, v251, 15
	v_readlane_b32 s50, v251, 16
	v_readlane_b32 s51, v251, 17
	v_mul_u32_u24_e32 v6, 0x90, v223
	v_mul_u32_u24_e32 v7, 0x70, v223
	s_addc_u32 s13, s73, 0
	v_lshl_add_u64 v[58:59], s[76:77], 0, v[40:41]
	s_mov_b64 s[6:7], 0x1800
	v_lshl_add_u32 v2, v2, 4, 16
	v_lshl_add_u64 v[42:43], s[50:51], 0, v[40:41]
	s_add_u32 s14, s72, 0x880000
	v_lshl_add_u64 v[62:63], v[58:59], 0, s[6:7]
	s_mov_b64 s[6:7], 0x2800
	v_lshl_add_u64 v[72:73], s[48:49], 0, v[40:41]
	v_add_u32_e32 v236, 0x5200, v2
	v_add3_u32 v3, v6, v7, 16
	v_add_u32_e32 v238, 0x7300, v2
	v_mul_u32_u24_e32 v2, 0x300000, v222
	v_readlane_b32 s36, v251, 22
	v_readlane_b32 s78, v251, 40
	v_readlane_b32 s79, v251, 41
	v_readlane_b32 s82, v251, 44
	v_readlane_b32 s83, v251, 45
	v_lshlrev_b32_e32 v10, 8, v222
	s_addc_u32 s15, s73, 0
	v_lshl_add_u64 v[66:67], v[58:59], 0, s[6:7]
	s_movk_i32 s8, 0xe00
	s_mov_b64 s[6:7], 0x3800
	v_add_u32_e32 v237, 0x1200, v3
	s_lshl_b32 s28, s64, 5
	v_or_b32_e32 v2, v2, v8
	v_mul_hi_u32_u24_e32 v3, 0x300000, v222
	v_readlane_b32 s37, v251, 23
	v_readlane_b32 s38, v251, 24
	v_readlane_b32 s39, v251, 25
	v_readlane_b32 s44, v251, 30
	v_readlane_b32 s45, v251, 31
	s_mov_b32 s16, 0x40c90fdb
	v_mov_b32_e32 v171, v41
	v_add_u32_e32 v1, 16, v40
	v_lshl_add_u64 v[44:45], s[78:79], 0, v[40:41]
	v_lshl_add_u64 v[46:47], s[82:83], 0, v[40:41]
	v_mul_u32_u24_e32 v232, 0x104, v223
	v_add_u32_e32 v233, 32, v223
	v_lshl_add_u64 v[70:71], v[58:59], 0, s[6:7]
	s_lshl_b32 s29, s74, 5
	v_lshl_add_u64 v[74:75], s[44:45], 0, v[2:3]
	s_movk_i32 s33, 0x63f
	s_mov_b32 s34, 0xf83f
	s_mov_b32 s17, 0x3f7fff90
	s_movk_i32 s35, 0x21f
	v_add_u32_e32 v239, v9, v10
	v_lshl_add_u64 v[76:77], s[38:39], 0, v[40:41]
	v_add_u32_e32 v250, 0xfffffe00, v170
	v_lshl_add_u32 v235, v222, 9, 16
	s_add_i32 s36, 16, 0x3200
	v_mov_b32_e32 v246, 1
	v_cmp_gt_u32_e64 s[6:7], s8, v4
	s_movk_i32 s37, 0x7fff
	s_movk_i32 s38, 0x900
	s_mov_b32 s39, s64
	v_cmp_gt_u32_e64 s[8:9], 64, v170
	s_add_i32 s18, s28, 0xfffe5e00
	s_add_i32 s20, s28, 0xfffe7e00
	s_mov_b64 s[22:23], 0x800
	s_mov_b32 s25, 0
	v_readlane_b32 s80, v251, 42
	v_readlane_b32 s81, v251, 43
	v_readlane_b32 s84, v251, 46
	v_readlane_b32 s85, v251, 47
	v_readlane_b32 s86, v251, 48
	v_readlane_b32 s87, v251, 49
	v_readlane_b32 s88, v251, 50
	v_readlane_b32 s89, v251, 51
	v_readlane_b32 s90, v251, 52
	v_readlane_b32 s91, v251, 53
	v_readlane_b32 s40, v251, 26
	v_readlane_b32 s41, v251, 27
	v_readlane_b32 s42, v251, 28
	v_readlane_b32 s43, v251, 29
	v_readlane_b32 s46, v251, 32
	v_readlane_b32 s47, v251, 33
	v_readlane_b32 s48, v251, 34
	v_readlane_b32 s49, v251, 35
	v_readlane_b32 s50, v251, 36
	v_readlane_b32 s51, v251, 37
	s_branch .LBB0_8
.LBB0_7:
	s_add_i32 s39, s39, s74
	s_add_i32 s18, s18, s29
	s_add_i32 s28, s28, s29
	s_add_i32 s20, s20, s29
	s_cmpk_gt_i32 s39, 0xd1f
	s_cbranch_scc1 .LBB0_77
.LBB0_8:
	s_cmpk_gt_i32 s39, 0x23f
	s_mov_b64 s[26:27], -1
	s_cbranch_scc0 .LBB0_75
	s_cmpk_gt_u32 s39, 0x33f
	s_cbranch_scc0 .LBB0_72
	s_cmpk_gt_u32 s39, 0x73f
	s_cbranch_scc0 .LBB0_69
	s_cmpk_gt_u32 s39, 0xb3f
	s_cbranch_scc0 .LBB0_66
	s_cmpk_gt_u32 s39, 0xbff
	s_cbranch_scc0 .LBB0_57
	s_cmpk_gt_u32 s39, 0xc0f
	s_cbranch_scc0 .LBB0_54
	s_cmpk_gt_u32 s39, 0xd0f
	s_cbranch_scc0 .LBB0_34
	s_add_i32 s101, s39, 0xfffff2f0
	s_and_b32 s100, s101, 1
	s_lshr_b32 s101, s101, 1
	s_add_i32 s99, s101, 0xd10
	s_lshl_b32 s98, s99, 5
	s_lshl_b32 s101, s101, 5
	s_mov_b64 s[26:27], 0
	v_mov_b64_e32 v[2:3], v[72:73]
	v_mov_b32_e32 v4, v250
	v_add_u32_e32 v5, 0x5200, v1
	s_barrier

.LBB0_21:
	s_or_b64 exec, exec, s[26:27]
	s_lshl_b32 s19, s99, 5
	s_add_i32 s19, s19, 0xfffe5e00
	s_mov_b64 s[26:27], 0
	v_mov_b32_e32 v4, v170
	s_branch .LBB0_23

.LBB0_28:
	v_add_u32_e32 v7, s19, v237
	ds_read_b128 v[8:11], v6
	ds_read_b128 v[12:15], v6 offset:256
	ds_read_b128 v[16:19], v6 offset:512
	ds_read_b128 v[20:23], v6 offset:768
	ds_read_b128 v[24:27], v6 offset:1024
	ds_read_b128 v[28:31], v6 offset:1280
	ds_read_b128 v[32:35], v6 offset:1536
	ds_read_b128 v[36:39], v6 offset:1792
	ds_read_b128 v[78:81], v6 offset:2048
	ds_read_b128 v[82:85], v6 offset:2304
	ds_read_b128 v[86:89], v6 offset:2560
	ds_read_b128 v[90:93], v6 offset:2816
	ds_read_b128 v[94:97], v6 offset:3072
	ds_read_b128 v[98:101], v6 offset:3328
	ds_read_b128 v[102:105], v6 offset:3584
	ds_read_b128 v[106:109], v6 offset:3840
	ds_read_b128 v[110:113], v7
	ds_read_b128 v[114:117], v7 offset:16
	ds_read_b128 v[118:121], v7 offset:32
	ds_read_b128 v[122:125], v7 offset:48
	s_add_i32 s19, s19, 64
	s_waitcnt lgkmcnt(3)
	v_pk_fma_f32 v[2:3], v[110:111], v[8:9], v[2:3] op_sel_hi:[0,1,1]
	v_pk_fma_f32 v[4:5], v[110:111], v[10:11], v[4:5] op_sel_hi:[0,1,1]
	v_pk_fma_f32 v[2:3], v[110:111], v[12:13], v[2:3] op_sel:[1,0,0]
	v_pk_fma_f32 v[4:5], v[110:111], v[14:15], v[4:5] op_sel:[1,0,0]
	v_mov_b32_e32 v8, v113
	v_pk_fma_f32 v[2:3], v[112:113], v[16:17], v[2:3] op_sel_hi:[0,1,1]
	v_pk_fma_f32 v[4:5], v[112:113], v[18:19], v[4:5] op_sel_hi:[0,1,1]
	v_pk_fma_f32 v[2:3], v[8:9], v[20:21], v[2:3] op_sel_hi:[0,1,1]
	v_pk_fma_f32 v[4:5], v[8:9], v[22:23], v[4:5] op_sel_hi:[0,1,1]
	s_waitcnt lgkmcnt(2)
	v_pk_fma_f32 v[2:3], v[114:115], v[24:25], v[2:3] op_sel_hi:[0,1,1]
	v_pk_fma_f32 v[4:5], v[114:115], v[26:27], v[4:5] op_sel_hi:[0,1,1]
	v_pk_fma_f32 v[2:3], v[114:115], v[28:29], v[2:3] op_sel:[1,0,0]
	v_pk_fma_f32 v[4:5], v[114:115], v[30:31], v[4:5] op_sel:[1,0,0]
	v_mov_b32_e32 v10, v117
	v_pk_fma_f32 v[2:3], v[116:117], v[32:33], v[2:3] op_sel_hi:[0,1,1]
	v_pk_fma_f32 v[4:5], v[116:117], v[34:35], v[4:5] op_sel_hi:[0,1,1]
	v_pk_fma_f32 v[2:3], v[10:11], v[36:37], v[2:3] op_sel_hi:[0,1,1]
	v_pk_fma_f32 v[4:5], v[10:11], v[38:39], v[4:5] op_sel_hi:[0,1,1]
	s_waitcnt lgkmcnt(1)
	v_pk_fma_f32 v[2:3], v[118:119], v[78:79], v[2:3] op_sel_hi:[0,1,1]
	v_pk_fma_f32 v[4:5], v[118:119], v[80:81], v[4:5] op_sel_hi:[0,1,1]
	v_pk_fma_f32 v[2:3], v[118:119], v[82:83], v[2:3] op_sel:[1,0,0]
	v_pk_fma_f32 v[4:5], v[118:119], v[84:85], v[4:5] op_sel:[1,0,0]
	v_mov_b32_e32 v40, v121
	v_pk_fma_f32 v[2:3], v[120:121], v[86:87], v[2:3] op_sel_hi:[0,1,1]
	v_pk_fma_f32 v[4:5], v[120:121], v[88:89], v[4:5] op_sel_hi:[0,1,1]
	v_pk_fma_f32 v[2:3], v[40:41], v[90:91], v[2:3] op_sel_hi:[0,1,1]
	v_pk_fma_f32 v[4:5], v[40:41], v[92:93], v[4:5] op_sel_hi:[0,1,1]
	s_waitcnt lgkmcnt(0)
	v_pk_fma_f32 v[2:3], v[122:123], v[94:95], v[2:3] op_sel_hi:[0,1,1]
	v_pk_fma_f32 v[4:5], v[122:123], v[96:97], v[4:5] op_sel_hi:[0,1,1]
	v_pk_fma_f32 v[2:3], v[122:123], v[98:99], v[2:3] op_sel:[1,0,0]
	v_pk_fma_f32 v[4:5], v[122:123], v[100:101], v[4:5] op_sel:[1,0,0]
	v_mov_b32_e32 v126, v125
	v_pk_fma_f32 v[2:3], v[124:125], v[102:103], v[2:3] op_sel_hi:[0,1,1]
	v_pk_fma_f32 v[4:5], v[124:125], v[104:105], v[4:5] op_sel_hi:[0,1,1]
	v_add_u32_e32 v6, 0x1000, v6
	s_cmpk_eq_i32 s19, 0x100
	v_pk_fma_f32 v[2:3], v[126:127], v[106:107], v[2:3] op_sel_hi:[0,1,1]
	v_pk_fma_f32 v[4:5], v[126:127], v[108:109], v[4:5] op_sel_hi:[0,1,1]
	s_cbranch_scc0 .LBB0_28
	ds_read_b128 v[6:9], v51 offset:46336
	s_lshl_b32 s24, s99, 10
	s_lshl_b64 s[26:27], s[24:25], 2
	s_add_u32 s19, s10, s26
	s_addc_u32 s21, s11, s27
	s_waitcnt lgkmcnt(0)
	v_mul_f32_e32 v2, v2, v6
	v_mul_f32_e32 v6, 0.15915494, v2
	v_rndne_f32_e32 v6, v6
	v_fmac_f32_e32 v2, 0xc0c90000, v6
	v_mul_f32_e32 v3, v3, v7
	v_fmac_f32_e32 v2, 0xbafdaa22, v6
	v_mul_f32_e32 v6, 0.15915494, v3
	v_rndne_f32_e32 v6, v6
	v_fmac_f32_e32 v3, 0xc0c90000, v6
	v_mul_f32_e32 v4, v4, v8
	v_fmac_f32_e32 v3, 0xbafdaa22, v6
	v_mul_f32_e32 v6, 0.15915494, v4
	v_rndne_f32_e32 v6, v6
	v_fmac_f32_e32 v4, 0xc0c90000, v6
	v_mul_f32_e32 v5, v5, v9
	v_fmac_f32_e32 v4, 0xbafdaa22, v6
	v_mul_f32_e32 v6, 0.15915494, v5
	v_rndne_f32_e32 v6, v6
	v_fmac_f32_e32 v5, 0xc0c90000, v6
	v_fmac_f32_e32 v5, 0xbafdaa22, v6
	v_mul_f32_e32 v2, 0.15915494, v2
	v_mul_f32_e32 v3, 0.15915494, v3
	v_mul_f32_e32 v4, 0.15915494, v4
	v_mul_f32_e32 v5, 0.15915494, v5
	s_add_u32 s26, s19, 0xff3f0000
	v_sin_f32_e32 v2, v2
	v_sin_f32_e32 v3, v3
	v_sin_f32_e32 v4, v4
	v_sin_f32_e32 v5, v5
	s_mov_b32 s19, s25
	s_addc_u32 s27, s21, -1
	s_lshl_b32 s40, s101, 2
	s_mov_b32 s41, 0
	v_readlane_b32 s42, v251, 58
	v_readlane_b32 s43, v251, 59
	s_add_u32 s40, s42, s40
	s_addc_u32 s41, s43, s41
	s_lshl_b32 s24, s100, 9
	s_mov_b64 s[50:51], 0
	s_cmp_lg_u32 s100, 0
	s_cselect_b64 s[42:43], -1, 0
	ds_write_b128 v228, v[2:5] offset:12800
	s_waitcnt lgkmcnt(0)
	s_barrier

.LBB0_31:
	v_mov_b32_e32 v249, s21
	ds_read_b128 v[2:5], v249
	ds_read_b128 v[6:9], v249 offset:16
	ds_read_b128 v[10:13], v249 offset:32
	ds_read_b128 v[14:17], v249 offset:48
	ds_read_b128 v[18:21], v249 offset:256
	s_waitcnt lgkmcnt(4)
	v_mov_b32_e32 v22, v2
	s_add_i32 s24, s98, s19
	s_add_i32 s44, s24, 0xfffe5e04
	s_waitcnt lgkmcnt(0)
	v_mov_b32_e32 v23, v18
	v_mov_b32_e32 v18, v3
	v_pk_mul_f32 v[2:3], v[80:81], v[18:19]
	v_mov_b32_e32 v18, v4
	v_pk_fma_f32 v[2:3], v[78:79], v[22:23], v[2:3]
	v_mov_b32_e32 v19, v20
	v_pk_fma_f32 v[2:3], v[82:83], v[18:19], v[2:3]
	v_mov_b32_e32 v20, v5
	v_pk_fma_f32 v[2:3], v[84:85], v[20:21], v[2:3]
	v_mov_b32_e32 v20, v6
	v_pk_add_f32 v[18:19], v[2:3], 0 op_sel_hi:[1,0]
	ds_read_b128 v[2:5], v249 offset:272
	v_mov_b32_e32 v6, v8
	v_mov_b32_e32 v8, v10
	s_waitcnt lgkmcnt(0)
	v_mov_b32_e32 v21, v2
	v_mov_b32_e32 v2, v7
	v_pk_mul_f32 v[2:3], v[88:89], v[2:3]
	v_mov_b32_e32 v7, v4
	v_pk_fma_f32 v[2:3], v[86:87], v[20:21], v[2:3]
	v_mov_b32_e32 v4, v9
	v_pk_fma_f32 v[2:3], v[90:91], v[6:7], v[2:3]
	s_nop 0
	v_pk_fma_f32 v[2:3], v[92:93], v[4:5], v[2:3]
	s_nop 0
	v_pk_add_f32 v[6:7], v[18:19], v[2:3]
	ds_read_b128 v[2:5], v249 offset:288
	s_waitcnt lgkmcnt(0)
	v_mov_b32_e32 v9, v2
	v_mov_b32_e32 v2, v11
	v_pk_mul_f32 v[2:3], v[96:97], v[2:3]
	s_nop 0
	v_pk_fma_f32 v[2:3], v[94:95], v[8:9], v[2:3]
	v_mov_b32_e32 v8, v12
	v_mov_b32_e32 v9, v4
	v_pk_fma_f32 v[2:3], v[98:99], v[8:9], v[2:3]
	v_mov_b32_e32 v4, v13
	v_pk_fma_f32 v[2:3], v[100:101], v[4:5], v[2:3]
	v_mov_b32_e32 v8, v14
	v_pk_add_f32 v[6:7], v[6:7], v[2:3]
	ds_read_b128 v[2:5], v249 offset:304
	s_waitcnt lgkmcnt(0)
	v_mov_b32_e32 v9, v2
	v_mov_b32_e32 v2, v15
	v_pk_mul_f32 v[2:3], v[104:105], v[2:3]
	s_nop 0
	v_pk_fma_f32 v[2:3], v[102:103], v[8:9], v[2:3]
	v_mov_b32_e32 v8, v16
	v_mov_b32_e32 v9, v4
	v_pk_fma_f32 v[2:3], v[106:107], v[8:9], v[2:3]
	v_mov_b32_e32 v4, v17
	v_pk_fma_f32 v[2:3], v[108:109], v[4:5], v[2:3]
	s_nop 0
	v_pk_add_f32 v[10:11], v[6:7], v[2:3]
	ds_read_b128 v[2:5], v249 offset:64
	ds_read_b128 v[6:9], v249 offset:320
	s_waitcnt lgkmcnt(1)
	v_mov_b32_e32 v12, v2
	s_waitcnt lgkmcnt(0)
	v_mov_b32_e32 v13, v6
	v_mov_b32_e32 v6, v3
	v_pk_mul_f32 v[2:3], v[112:113], v[6:7]
	v_mov_b32_e32 v6, v4
	v_pk_fma_f32 v[2:3], v[110:111], v[12:13], v[2:3]
	v_mov_b32_e32 v7, v8
	v_pk_fma_f32 v[2:3], v[114:115], v[6:7], v[2:3]
	v_mov_b32_e32 v8, v5
	v_pk_fma_f32 v[2:3], v[116:117], v[8:9], v[2:3]
	s_nop 0
	v_pk_add_f32 v[10:11], v[10:11], v[2:3]
	ds_read_b128 v[2:5], v249 offset:80
	ds_read_b128 v[6:9], v249 offset:336
	s_waitcnt lgkmcnt(1)
	v_mov_b32_e32 v12, v2
	s_waitcnt lgkmcnt(0)
	v_mov_b32_e32 v13, v6
	v_mov_b32_e32 v6, v3
	v_pk_mul_f32 v[2:3], v[120:121], v[6:7]
	v_mov_b32_e32 v6, v4
	v_pk_fma_f32 v[2:3], v[118:119], v[12:13], v[2:3]
	v_mov_b32_e32 v7, v8
	v_pk_fma_f32 v[2:3], v[122:123], v[6:7], v[2:3]
	v_mov_b32_e32 v8, v5
	v_pk_fma_f32 v[2:3], v[124:125], v[8:9], v[2:3]
	s_nop 0
	v_pk_add_f32 v[214:215], v[10:11], v[2:3]
	ds_read_b128 v[2:5], v249 offset:512
	ds_read_b128 v[6:9], v249 offset:768
	s_waitcnt lgkmcnt(1)
	v_mov_b32_e32 v10, v2
	s_waitcnt lgkmcnt(0)
	v_mov_b32_e32 v11, v6
	v_mov_b32_e32 v6, v3
	v_pk_mul_f32 v[2:3], v[80:81], v[6:7]
	v_mov_b32_e32 v6, v4
	v_pk_fma_f32 v[2:3], v[78:79], v[10:11], v[2:3]
	v_mov_b32_e32 v7, v8
	v_pk_fma_f32 v[2:3], v[82:83], v[6:7], v[2:3]
	v_mov_b32_e32 v8, v5
	v_pk_fma_f32 v[2:3], v[84:85], v[8:9], v[2:3]
	s_nop 0
	v_pk_add_f32 v[10:11], v[2:3], 0 op_sel_hi:[1,0]
	ds_read_b128 v[2:5], v249 offset:528
	ds_read_b128 v[6:9], v249 offset:784
	s_waitcnt lgkmcnt(1)
	v_mov_b32_e32 v12, v2
	s_waitcnt lgkmcnt(0)
	v_mov_b32_e32 v13, v6
	v_mov_b32_e32 v6, v3
	v_pk_mul_f32 v[2:3], v[88:89], v[6:7]
	v_mov_b32_e32 v6, v4
	v_pk_fma_f32 v[2:3], v[86:87], v[12:13], v[2:3]
	v_mov_b32_e32 v7, v8
	v_pk_fma_f32 v[2:3], v[90:91], v[6:7], v[2:3]
	v_mov_b32_e32 v8, v5
	v_pk_fma_f32 v[2:3], v[92:93], v[8:9], v[2:3]
	s_nop 0
	v_pk_add_f32 v[10:11], v[10:11], v[2:3]
	ds_read_b128 v[2:5], v249 offset:544
	ds_read_b128 v[6:9], v249 offset:800
	s_waitcnt lgkmcnt(1)
	v_mov_b32_e32 v12, v2
	s_waitcnt lgkmcnt(0)
	v_mov_b32_e32 v13, v6
	v_mov_b32_e32 v6, v3
	v_pk_mul_f32 v[2:3], v[96:97], v[6:7]
	v_mov_b32_e32 v6, v4
	v_pk_fma_f32 v[2:3], v[94:95], v[12:13], v[2:3]
	v_mov_b32_e32 v7, v8
	v_pk_fma_f32 v[2:3], v[98:99], v[6:7], v[2:3]
	v_mov_b32_e32 v8, v5
	v_pk_fma_f32 v[2:3], v[100:101], v[8:9], v[2:3]
	s_nop 0
	v_pk_add_f32 v[10:11], v[10:11], v[2:3]
	ds_read_b128 v[2:5], v249 offset:560
	ds_read_b128 v[6:9], v249 offset:816
	s_waitcnt lgkmcnt(1)
	v_mov_b32_e32 v12, v2
	s_waitcnt lgkmcnt(0)
	v_mov_b32_e32 v13, v6
	v_mov_b32_e32 v6, v3
	v_pk_mul_f32 v[2:3], v[104:105], v[6:7]
	v_mov_b32_e32 v6, v4
	v_pk_fma_f32 v[2:3], v[102:103], v[12:13], v[2:3]
	v_mov_b32_e32 v7, v8
	v_pk_fma_f32 v[2:3], v[106:107], v[6:7], v[2:3]
	v_mov_b32_e32 v8, v5
	v_pk_fma_f32 v[2:3], v[108:109], v[8:9], v[2:3]
	s_nop 0
	v_pk_add_f32 v[10:11], v[10:11], v[2:3]
	ds_read_b128 v[2:5], v249 offset:576
	ds_read_b128 v[6:9], v249 offset:832
	s_waitcnt lgkmcnt(1)
	v_mov_b32_e32 v12, v2
	s_waitcnt lgkmcnt(0)
	v_mov_b32_e32 v13, v6
	v_mov_b32_e32 v6, v3
	v_pk_mul_f32 v[2:3], v[112:113], v[6:7]
	v_mov_b32_e32 v6, v4
	v_pk_fma_f32 v[2:3], v[110:111], v[12:13], v[2:3]
	v_mov_b32_e32 v7, v8
	v_pk_fma_f32 v[2:3], v[114:115], v[6:7], v[2:3]
	v_mov_b32_e32 v8, v5
	v_pk_fma_f32 v[2:3], v[116:117], v[8:9], v[2:3]
	s_nop 0
	v_pk_add_f32 v[10:11], v[10:11], v[2:3]
	ds_read_b128 v[2:5], v249 offset:592
	ds_read_b128 v[6:9], v249 offset:848
	s_waitcnt lgkmcnt(1)
	v_mov_b32_e32 v12, v2
	s_waitcnt lgkmcnt(0)
	v_mov_b32_e32 v13, v6
	v_mov_b32_e32 v6, v3
	v_pk_mul_f32 v[2:3], v[120:121], v[6:7]
	v_mov_b32_e32 v6, v4
	v_pk_fma_f32 v[2:3], v[118:119], v[12:13], v[2:3]
	v_mov_b32_e32 v7, v8
	v_pk_fma_f32 v[2:3], v[122:123], v[6:7], v[2:3]
	v_mov_b32_e32 v8, v5
	v_pk_fma_f32 v[2:3], v[124:125], v[8:9], v[2:3]
	s_nop 0
	v_pk_add_f32 v[210:211], v[10:11], v[2:3]
	ds_read_b128 v[2:5], v249 offset:96
	ds_read_b128 v[6:9], v249 offset:352
	s_waitcnt lgkmcnt(1)
	v_mov_b32_e32 v10, v2
	s_waitcnt lgkmcnt(0)
	v_mov_b32_e32 v11, v6
	v_mov_b32_e32 v6, v3
	v_pk_mul_f32 v[2:3], v[128:129], v[6:7]
	v_mov_b32_e32 v6, v4
	v_pk_fma_f32 v[2:3], v[126:127], v[10:11], v[2:3]
	v_mov_b32_e32 v7, v8
	v_pk_fma_f32 v[2:3], v[130:131], v[6:7], v[2:3]
	v_mov_b32_e32 v8, v5
	v_pk_fma_f32 v[218:219], v[132:133], v[8:9], v[2:3]
	ds_read_b128 v[2:5], v249 offset:608
	ds_read_b128 v[6:9], v249 offset:864
	s_waitcnt lgkmcnt(1)
	v_mov_b32_e32 v10, v2
	s_waitcnt lgkmcnt(0)
	v_mov_b32_e32 v11, v6
	v_mov_b32_e32 v6, v3
	v_pk_mul_f32 v[2:3], v[128:129], v[6:7]
	v_mov_b32_e32 v6, v4
	v_pk_fma_f32 v[2:3], v[126:127], v[10:11], v[2:3]
	v_mov_b32_e32 v7, v8
	v_pk_fma_f32 v[2:3], v[130:131], v[6:7], v[2:3]
	v_mov_b32_e32 v8, v5
	v_pk_fma_f32 v[212:213], v[132:133], v[8:9], v[2:3]
	ds_read_b128 v[6:9], v249 offset:112
	ds_read_b128 v[20:23], v249 offset:368
	ds_read_b128 v[10:13], v249 offset:624
	ds_read_b128 v[2:5], v249 offset:880
	s_waitcnt lgkmcnt(3)
	v_mov_b32_e32 v14, v6
	s_waitcnt lgkmcnt(2)
	v_mov_b32_e32 v15, v20
	v_mov_b32_e32 v20, v7
	v_pk_mul_f32 v[6:7], v[136:137], v[20:21]
	s_nop 0
	v_pk_fma_f32 v[6:7], v[134:135], v[14:15], v[6:7]
	v_mov_b32_e32 v14, v8
	v_mov_b32_e32 v15, v22
	v_pk_fma_f32 v[240:241], v[138:139], v[14:15], v[6:7]
	s_waitcnt lgkmcnt(0)
	v_mov_b32_e32 v7, v2
	v_mov_b32_e32 v2, v11
	v_mov_b32_e32 v6, v10
	v_pk_mul_f32 v[2:3], v[136:137], v[2:3]
	v_mov_b32_e32 v22, v9
	v_pk_fma_f32 v[2:3], v[134:135], v[6:7], v[2:3]
	v_mov_b32_e32 v6, v12
	v_mov_b32_e32 v7, v4
	v_pk_fma_f32 v[216:217], v[138:139], v[6:7], v[2:3]
	v_mov_b32_e32 v4, v13
	ds_read_b128 v[24:27], v249 offset:128
	ds_read_b128 v[28:31], v249 offset:384
	ds_read_b128 v[6:9], v249 offset:640
	ds_read_b128 v[10:13], v249 offset:896
	v_pk_fma_f32 v[22:23], v[140:141], v[22:23], v[240:241]
	s_waitcnt lgkmcnt(3)
	v_mov_b32_e32 v2, v24
	s_waitcnt lgkmcnt(2)
	v_mov_b32_e32 v3, v28
	v_mov_b32_e32 v28, v25
	v_pk_mul_f32 v[14:15], v[144:145], v[28:29]
	v_mov_b32_e32 v244, v26
	v_pk_fma_f32 v[242:243], v[142:143], v[2:3], v[14:15]
	ds_read_b128 v[32:35], v249 offset:144
	ds_read_b128 v[36:39], v249 offset:400
	ds_read_b128 v[14:17], v249 offset:656
	ds_read_b128 v[18:21], v249 offset:912
	s_waitcnt lgkmcnt(4)
	v_mov_b32_e32 v3, v10
	v_mov_b32_e32 v10, v7
	v_mov_b32_e32 v2, v6
	v_pk_mul_f32 v[6:7], v[144:145], v[10:11]
	s_waitcnt lgkmcnt(0)
	v_mov_b32_e32 v11, v18
	v_mov_b32_e32 v18, v15
	v_mov_b32_e32 v245, v30
	v_mov_b32_e32 v10, v14
	v_pk_mul_f32 v[14:15], v[152:153], v[18:19]
	v_pk_add_f32 v[18:19], v[214:215], v[218:219]
	v_mov_b32_e32 v221, v36
	v_mov_b32_e32 v36, v33
	v_pk_add_f32 v[18:19], v[18:19], v[22:23]
	v_pk_fma_f32 v[22:23], v[146:147], v[244:245], v[242:243]
	v_mov_b32_e32 v30, v27
	v_mov_b32_e32 v220, v32
	v_pk_mul_f32 v[32:33], v[152:153], v[36:37]
	v_pk_fma_f32 v[22:23], v[148:149], v[30:31], v[22:23]
	v_mov_b32_e32 v26, v34
	v_pk_add_f32 v[18:19], v[18:19], v[22:23]
	v_pk_fma_f32 v[22:23], v[150:151], v[220:221], v[32:33]
	v_mov_b32_e32 v27, v38
	v_mov_b32_e32 v38, v35
	ds_read_b128 v[30:33], v249 offset:160
	ds_read_b128 v[34:37], v249 offset:416
	v_pk_fma_f32 v[22:23], v[154:155], v[26:27], v[22:23]
	v_pk_fma_f32 v[24:25], v[142:143], v[2:3], v[6:7]
	v_pk_fma_f32 v[22:23], v[156:157], v[38:39], v[22:23]
	v_cvt_f32_u32_e32 v2, s44
	v_pk_add_f32 v[18:19], v[18:19], v[22:23]
	s_waitcnt lgkmcnt(0)
	v_mov_b32_e32 v23, v34
	v_mov_b32_e32 v34, v31
	v_mov_b32_e32 v22, v30
	v_pk_mul_f32 v[26:27], v[160:161], v[34:35]
	s_add_i32 s44, s24, 0xfffe5e05
	v_pk_fma_f32 v[22:23], v[158:159], v[22:23], v[26:27]
	v_mov_b32_e32 v26, v32
	v_mov_b32_e32 v27, v36
	v_pk_fma_f32 v[22:23], v[162:163], v[26:27], v[22:23]
	v_mov_b32_e32 v36, v33
	v_pk_fma_f32 v[22:23], v[164:165], v[36:37], v[22:23]
	ds_read_b128 v[30:33], v249 offset:176
	ds_read_b128 v[34:37], v249 offset:432
	v_pk_add_f32 v[18:19], v[18:19], v[22:23]
	v_cvt_f32_u32_e32 v3, s44
	v_mul_f32_e32 v2, 0xbb800000, v2
	s_waitcnt lgkmcnt(1)
	v_mov_b32_e32 v22, v30
	s_waitcnt lgkmcnt(0)
	v_mov_b32_e32 v23, v34
	v_mov_b32_e32 v34, v31
	v_pk_mul_f32 v[26:27], v[168:169], v[34:35]
	v_mul_f32_e32 v3, 0xbb800000, v3
	v_pk_fma_f32 v[22:23], v[166:167], v[22:23], v[26:27]
	v_mov_b32_e32 v26, v32
	v_mov_b32_e32 v27, v36
	v_pk_fma_f32 v[22:23], v[172:173], v[26:27], v[22:23]
	v_mov_b32_e32 v36, v33
	v_pk_fma_f32 v[22:23], v[174:175], v[36:37], v[22:23]
	ds_read_b128 v[30:33], v249 offset:192
	ds_read_b128 v[34:37], v249 offset:448
	v_pk_add_f32 v[18:19], v[18:19], v[22:23]
	v_mul_f32_e64 v2, |v247|, v2
	v_mul_f32_e64 v3, |v247|, v3
	s_waitcnt lgkmcnt(1)
	v_mov_b32_e32 v22, v30
	s_waitcnt lgkmcnt(0)
	v_mov_b32_e32 v23, v34
	v_mov_b32_e32 v34, v31
	v_pk_mul_f32 v[26:27], v[178:179], v[34:35]
	v_mul_f32_e32 v2, 0x3fb8aa3b, v2
	v_pk_fma_f32 v[22:23], v[176:177], v[22:23], v[26:27]
	v_mov_b32_e32 v26, v32
	v_mov_b32_e32 v27, v36
	v_pk_fma_f32 v[22:23], v[180:181], v[26:27], v[22:23]
	v_mov_b32_e32 v36, v33
	v_pk_fma_f32 v[22:23], v[182:183], v[36:37], v[22:23]
	ds_read_b128 v[30:33], v249 offset:208
	ds_read_b128 v[34:37], v249 offset:464
	v_pk_add_f32 v[18:19], v[18:19], v[22:23]
	v_mul_f32_e32 v3, 0x3fb8aa3b, v3
	v_exp_f32_e32 v2, v2
	s_waitcnt lgkmcnt(1)
	v_mov_b32_e32 v22, v30
	s_waitcnt lgkmcnt(0)
	v_mov_b32_e32 v23, v34
	v_mov_b32_e32 v34, v31
	v_pk_mul_f32 v[26:27], v[186:187], v[34:35]
	v_exp_f32_e32 v3, v3
	v_pk_fma_f32 v[22:23], v[184:185], v[22:23], v[26:27]
	v_mov_b32_e32 v26, v32
	v_mov_b32_e32 v27, v36
	v_pk_fma_f32 v[22:23], v[188:189], v[26:27], v[22:23]
	v_mov_b32_e32 v36, v33
	v_pk_fma_f32 v[22:23], v[190:191], v[36:37], v[22:23]
	ds_read_b128 v[30:33], v249 offset:224
	ds_read_b128 v[34:37], v249 offset:480
	v_pk_add_f32 v[18:19], v[18:19], v[22:23]
	s_add_i32 s44, s24, 0xfffe5e06
	v_cvt_f32_u32_e32 v6, s44
	s_waitcnt lgkmcnt(1)
	v_mov_b32_e32 v22, v30
	s_waitcnt lgkmcnt(0)
	v_mov_b32_e32 v23, v34
	v_mov_b32_e32 v34, v31
	v_pk_mul_f32 v[26:27], v[194:195], v[34:35]
	s_add_i32 s44, s24, 0xfffe5e07
	v_pk_fma_f32 v[22:23], v[192:193], v[22:23], v[26:27]
	v_mov_b32_e32 v26, v32
	v_mov_b32_e32 v27, v36
	v_pk_fma_f32 v[22:23], v[196:197], v[26:27], v[22:23]
	v_mov_b32_e32 v36, v33
	v_pk_fma_f32 v[22:23], v[198:199], v[36:37], v[22:23]
	ds_read_b128 v[30:33], v249 offset:240
	ds_read_b128 v[34:37], v249 offset:496
	v_pk_add_f32 v[18:19], v[18:19], v[22:23]
	s_cmp_eq_u32 s24, 0x1a1fc
	v_mov_b32_e32 v28, v8
	s_waitcnt lgkmcnt(1)
	v_mov_b32_e32 v22, v30
	s_waitcnt lgkmcnt(0)
	v_mov_b32_e32 v23, v34
	v_mov_b32_e32 v34, v31
	v_pk_mul_f32 v[26:27], v[202:203], v[34:35]
	v_mov_b32_e32 v29, v12
	v_pk_fma_f32 v[22:23], v[200:201], v[22:23], v[26:27]
	v_mov_b32_e32 v26, v32
	v_mov_b32_e32 v27, v36
	v_pk_fma_f32 v[22:23], v[204:205], v[26:27], v[22:23]
	v_mov_b32_e32 v36, v33
	v_pk_fma_f32 v[22:23], v[206:207], v[36:37], v[22:23]
	v_cvt_f32_u32_e32 v7, s44
	v_pk_add_f32 v[18:19], v[18:19], v[22:23]
	s_cselect_b64 s[44:45], -1, 0
	v_pk_mul_f32 v[2:3], v[2:3], v[18:19]
	v_pk_add_f32 v[22:23], v[210:211], v[212:213]
	v_pk_mul_f32 v[18:19], v[2:3], v[2:3]
	v_pk_fma_f32 v[4:5], v[140:141], v[4:5], v[216:217]
	s_and_b64 vcc, s[42:43], s[44:45]
	v_add_f32_e32 v8, v248, v18
	v_pk_add_f32 v[4:5], v[22:23], v[4:5]
	v_pk_fma_f32 v[22:23], v[146:147], v[28:29], v[24:25]
	v_mov_b32_e32 v12, v9
	v_cndmask_b32_e32 v18, v8, v248, vcc
	v_pk_fma_f32 v[8:9], v[148:149], v[12:13], v[22:23]
	v_mul_f32_e32 v6, 0xbb800000, v6
	v_pk_add_f32 v[4:5], v[4:5], v[8:9]
	v_pk_fma_f32 v[8:9], v[150:151], v[10:11], v[14:15]
	v_mov_b32_e32 v10, v16
	v_mov_b32_e32 v11, v20
	v_pk_fma_f32 v[8:9], v[154:155], v[10:11], v[8:9]
	v_mov_b32_e32 v20, v17
	v_pk_fma_f32 v[8:9], v[156:157], v[20:21], v[8:9]
	v_mul_f32_e32 v7, 0xbb800000, v7
	v_pk_add_f32 v[4:5], v[4:5], v[8:9]
	ds_read_b128 v[8:11], v249 offset:672
	ds_read_b128 v[12:15], v249 offset:928
	v_mul_f32_e64 v6, |v247|, v6
	v_mul_f32_e64 v7, |v247|, v7
	v_mul_f32_e32 v6, 0x3fb8aa3b, v6
	s_waitcnt lgkmcnt(1)
	v_mov_b32_e32 v16, v8
	s_waitcnt lgkmcnt(0)
	v_mov_b32_e32 v17, v12
	v_mov_b32_e32 v12, v9
	v_pk_mul_f32 v[8:9], v[160:161], v[12:13]
	v_mov_b32_e32 v12, v10
	v_pk_fma_f32 v[8:9], v[158:159], v[16:17], v[8:9]
	v_mov_b32_e32 v13, v14
	v_pk_fma_f32 v[8:9], v[162:163], v[12:13], v[8:9]
	v_mov_b32_e32 v14, v11
	v_pk_fma_f32 v[8:9], v[164:165], v[14:15], v[8:9]
	v_mul_f32_e32 v7, 0x3fb8aa3b, v7
	v_pk_add_f32 v[4:5], v[4:5], v[8:9]
	ds_read_b128 v[8:11], v249 offset:688
	ds_read_b128 v[12:15], v249 offset:944
	v_exp_f32_e32 v6, v6
	v_exp_f32_e32 v7, v7
	s_add_i32 s19, s19, 4
	s_waitcnt lgkmcnt(1)
	v_mov_b32_e32 v16, v8
	s_waitcnt lgkmcnt(0)
	v_mov_b32_e32 v17, v12
	v_mov_b32_e32 v12, v9
	v_pk_mul_f32 v[8:9], v[168:169], v[12:13]
	v_mov_b32_e32 v12, v10
	v_pk_fma_f32 v[8:9], v[166:167], v[16:17], v[8:9]
	v_mov_b32_e32 v13, v14
	v_pk_fma_f32 v[8:9], v[172:173], v[12:13], v[8:9]
	v_mov_b32_e32 v14, v11
	v_pk_fma_f32 v[8:9], v[174:175], v[14:15], v[8:9]
	s_addk_i32 s21, 0x400
	v_pk_add_f32 v[4:5], v[4:5], v[8:9]
	ds_read_b128 v[8:11], v249 offset:704
	ds_read_b128 v[12:15], v249 offset:960
	s_cmp_lt_u32 s19, 28
	s_waitcnt lgkmcnt(1)
	v_mov_b32_e32 v16, v8
	s_waitcnt lgkmcnt(0)
	v_mov_b32_e32 v17, v12
	v_mov_b32_e32 v12, v9
	v_pk_mul_f32 v[8:9], v[178:179], v[12:13]
	v_mov_b32_e32 v12, v10
	v_pk_fma_f32 v[8:9], v[176:177], v[16:17], v[8:9]
	v_mov_b32_e32 v13, v14
	v_pk_fma_f32 v[8:9], v[180:181], v[12:13], v[8:9]
	v_mov_b32_e32 v14, v11
	v_pk_fma_f32 v[8:9], v[182:183], v[14:15], v[8:9]
	s_nop 0
	v_pk_add_f32 v[4:5], v[4:5], v[8:9]
	ds_read_b128 v[8:11], v249 offset:720
	ds_read_b128 v[12:15], v249 offset:976
	s_waitcnt lgkmcnt(1)
	v_mov_b32_e32 v16, v8
	s_waitcnt lgkmcnt(0)
	v_mov_b32_e32 v17, v12
	v_mov_b32_e32 v12, v9
	v_pk_mul_f32 v[8:9], v[186:187], v[12:13]
	v_mov_b32_e32 v12, v10
	v_pk_fma_f32 v[8:9], v[184:185], v[16:17], v[8:9]
	v_mov_b32_e32 v13, v14
	v_pk_fma_f32 v[8:9], v[188:189], v[12:13], v[8:9]
	v_mov_b32_e32 v14, v11
	v_pk_fma_f32 v[8:9], v[190:191], v[14:15], v[8:9]
	s_nop 0
	v_pk_add_f32 v[4:5], v[4:5], v[8:9]
	ds_read_b128 v[8:11], v249 offset:736
	ds_read_b128 v[12:15], v249 offset:992
	s_waitcnt lgkmcnt(1)
	v_mov_b32_e32 v16, v8
	s_waitcnt lgkmcnt(0)
	v_mov_b32_e32 v17, v12
	v_mov_b32_e32 v12, v9
	v_pk_mul_f32 v[8:9], v[194:195], v[12:13]
	v_mov_b32_e32 v12, v10
	v_pk_fma_f32 v[8:9], v[192:193], v[16:17], v[8:9]
	v_mov_b32_e32 v13, v14
	v_pk_fma_f32 v[8:9], v[196:197], v[12:13], v[8:9]
	v_mov_b32_e32 v14, v11
	v_pk_fma_f32 v[8:9], v[198:199], v[14:15], v[8:9]
	s_nop 0
	v_pk_add_f32 v[4:5], v[4:5], v[8:9]
	ds_read_b128 v[8:11], v249 offset:752
	ds_read_b128 v[12:15], v249 offset:1008
	s_waitcnt lgkmcnt(1)
	v_mov_b32_e32 v16, v8
	s_waitcnt lgkmcnt(0)
	v_mov_b32_e32 v17, v12
	v_mov_b32_e32 v12, v9
	v_pk_mul_f32 v[8:9], v[202:203], v[12:13]
	v_mov_b32_e32 v12, v10
	v_pk_fma_f32 v[8:9], v[200:201], v[16:17], v[8:9]
	v_mov_b32_e32 v13, v14
	v_pk_fma_f32 v[8:9], v[204:205], v[12:13], v[8:9]
	v_mov_b32_e32 v14, v11
	v_pk_fma_f32 v[8:9], v[206:207], v[14:15], v[8:9]
	s_nop 0
	v_pk_add_f32 v[4:5], v[4:5], v[8:9]
	s_nop 0
	v_pk_mul_f32 v[4:5], v[6:7], v[4:5]
	global_store_dwordx4 v[208:209], v[2:5], off
	v_pk_mul_f32 v[6:7], v[4:5], v[4:5]
	v_lshl_add_u64 v[208:209], v[208:209], 0, 16
	v_add_f32_e32 v6, v19, v6
	v_add_f32_e32 v6, v6, v7
	v_add_f32_e32 v248, v18, v6
	s_cbranch_scc1 .LBB0_31
	v_lshl_add_u64 v[2:3], v[40:41], 2, s[26:27]
	s_movk_i32 s24, 0x200
	s_mov_b64 s[50:51], 0
	s_andn2_b64 vcc, exec, s[48:49]
	s_mov_b64 s[42:43], -1
	global_store_dword v[2:3], v248, off
	s_cbranch_vccnz .LBB0_30
	s_mov_b64 s[26:27], 0
